# conv-tile epilogue: conv_w tap rows + gain row loads issued at the top of the epilogue (before the boundary-row exchange barrier) instead of after it
# baseline (speedup 1.0000x reference)
; __device__ __forceinline__ void st_wt16f(void* p, wt_f32x4 v) { asm volatile("global_store_dwordx4 %0, %1, off sc1\n\ts_nop 1" :: "v"(p), "v"(v) : "memory"); }
; #define PG8_LAS __attribute__((address_space(3)))
;     __device__ __forceinline__ void operator()(f32x4 (&acc)[2][2][4][2], const Unit& u, int wr, int wc, int fr, int fq, PG8_LAS unsigned char* lds) const {
;         if (u.pn >= 9) {
;             const int lane = threadIdx.x & 63, j = u.pn - 9, col = j * 64 + wc * 16 + fq * 4;
;             PG8_LAS f32x4* XB = (PG8_LAS f32x4*)(lds + STAGE_BYTES + 2048);
; #pragma unroll
;             for (int ai = 0; ai < 2; ++ai)
; #pragma unroll
;                 for (int m = 0; m < 4; ++m) acc[ai][0][m][1] *= acc[ai][1][m][0];
;             if (fr >= 14) {
; #pragma unroll
;                 for (int ai = 0; ai < 2; ++ai) XB[((2 * ai + wr) * 4 + wc) * 8 + fq * 2 + (fr - 14)] = acc[ai][0][3][1];
;                 if (wr == 1) st_wt16f(HALO + ((size_t)u.pm * 2 + (fr - 14)) * 1024 + col, acc[1][0][3][1]);
;             }
;             asm volatile("s_waitcnt lgkmcnt(0)" ::: "memory"); __builtin_amdgcn_s_barrier(); asm volatile("" ::: "memory");
;             const f32x4 w0 = *(const f32x4*)(conv_w + col), w1 = *(const f32x4*)(conv_w + 1024 + col), w2 = *(const f32x4*)(conv_w + 2048 + col), gn = *(const f32x4*)(gain_c + col);
.LBB0_139:
	s_add_i32 s2, s60, -9
	v_pk_mul_f32 v[136:137], v[78:79], v[74:75]
	v_pk_mul_f32 v[134:135], v[76:77], v[72:73]
	v_pk_mul_f32 v[66:67], v[66:67], v[54:55]
	v_pk_mul_f32 v[64:65], v[64:65], v[52:53]
	v_lshl_or_b32 v146, s2, 6, v175
	v_readlane_b32 s42, v253, 10
	v_readlane_b32 s43, v253, 11
	v_readlane_b32 s46, v253, 14
	v_readlane_b32 s47, v253, 15
	v_lshlrev_b64 v[208:209], 2, v[146:147]
	v_lshl_add_u64 v[210:211], s[76:77], 0, v[208:209]
	v_lshl_add_u64 v[212:213], s[78:79], 0, v[208:209]
	v_lshl_add_u64 v[214:215], s[42:43], 0, v[208:209]
	v_lshl_add_u64 v[216:217], s[46:47], 0, v[208:209]
	global_load_dwordx4 v[82:85], v[214:215], off
	global_load_dwordx4 v[76:79], v[210:211], off
	global_load_dwordx4 v[72:75], v[212:213], off
	global_load_dwordx4 v[52:55], v[216:217], off
	s_and_saveexec_b64 s[0:1], s[14:15]
	s_cbranch_execz .LBB0_142
	s_andn2_b64 vcc, exec, s[62:63]
	ds_write_b128 v177, v[134:137]
	ds_write_b128 v176, v[64:67] offset:800
	s_cbranch_vccnz .LBB0_142
	s_ashr_i32 s75, s74, 31
	s_lshl_b64 s[16:17], s[74:75], 13
	v_lshl_add_u64 v[218:219], v[150:151], 0, s[16:17]
	v_lshl_add_u64 v[218:219], v[146:147], 2, v[218:219]
	global_store_dwordx4 v[218:219], v[64:67], off sc1
	s_nop 1
.LBB0_142:
	s_or_b64 exec, exec, s[0:1]
	v_readlane_b32 s36, v253, 4
	v_readlane_b32 s42, v253, 10
	v_readlane_b32 s43, v253, 11
	s_waitcnt lgkmcnt(0)
	s_barrier
	v_readlane_b32 s46, v253, 14
	v_readlane_b32 s47, v253, 15
	v_mov_b32_e32 v138, 0
	s_andn2_b64 vcc, exec, s[72:73]
	v_mov_b32_e32 v139, 0
	v_mov_b32_e32 v140, 0
	v_mov_b32_e32 v141, 0
	v_readlane_b32 s37, v253, 5
	v_readlane_b32 s38, v253, 6
	v_readlane_b32 s39, v253, 7
	v_readlane_b32 s40, v253, 8
	v_readlane_b32 s41, v253, 9
	v_readlane_b32 s44, v253, 12
	v_readlane_b32 s45, v253, 13
	v_readlane_b32 s48, v253, 16
	v_readlane_b32 s49, v253, 17
	v_readlane_b32 s50, v253, 18
	v_readlane_b32 s51, v253, 19
	s_cbranch_vccnz .LBB0_144
	ds_read_b128 v[138:141], v179
